# P7 epilogue wait relaxed to vmcnt(6): the hoisted rowsq loads are older than the 6 LDS-DMA prefetches of the next tile, which may stay in flight
# speedup vs baseline: 1.0056x; 1.0022x over previous
; #define PG8_STAGE(bufoff, gbase, voff) do { _Pragma("unroll") for (int _i = 0; _i < 2; ++_i) \
;         __builtin_amdgcn_global_load_lds((const unsigned*)((const char*)(gbase) + (voff)[_i]), (LAS unsigned*)(lds + (bufoff) + ldsw + _i * 8192), 16, 0, 0); } while (0)
; #define PG8_LDA(dst, b, h) do { _Pragma("unroll") for (int m = 0; m < 4; ++m) _Pragma("unroll") for (int k = 0; k < 2; ++k) dst[m][k] = *(const LAS bf16x8*)(lds + PG8_SA(b, h) + aoff + m * 2048 + k * 1024); } while (0)
; #define PG8_LDB(dst, b, h) do { _Pragma("unroll") for (int n = 0; n < 2; ++n) _Pragma("unroll") for (int k = 0; k < 2; ++k) dst[n][k] = *(const LAS bf16x8*)(lds + PG8_SB(b, h) + boff + n * 2048 + k * 1024); } while (0)
; #define PG8_MMA(ai, bj, At, Bt) do { __builtin_amdgcn_s_setprio(1); _Pragma("unroll") for (int m = 0; m < 4; ++m) _Pragma("unroll") for (int n = 0; n < 2; ++n) _Pragma("unroll") for (int k = 0; k < 2; ++k) \
;         acc[ai][bj][m][n] = __builtin_amdgcn_mfma_f32_16x16x32_bf16(Bt[n][k], At[m][k], acc[ai][bj][m][n], 0, 0, 0); __builtin_amdgcn_s_setprio(0); } while (0)
; #define PG8_WAIT_V(n) asm volatile("s_waitcnt vmcnt(" #n ")" ::: "memory")
; #define PG8_WAIT_L(n) asm volatile("s_waitcnt lgkmcnt(" #n ")" ::: "memory")
; template <class Epi, class Sched>
; __device__ __forceinline__ void gemm_phase(LAS unsigned char* lds, const Gemm g, const Sched& S, const Epi& E) {
;     ...
;         for (int t = 0; t < nt; t += 2) {
;             const bool last = (t == nt - 2);
;             const char* a1 = cA + (size_t)(t + 1) * kstep;
;             const char* a2 = last ? nA : cA + (size_t)(t + 2) * kstep; const char* b2 = last ? nB : cB + (size_t)(t + 2) * kstep;
;             const char* a3 = a2 + kstep; const char* b3 = b2 + kstep;
;             PG8_LDB(B0, 0, 0); PG8_SCHED; PG8_LDA(At, 0, 0); PG8_STAGE(PG8_SA(1, 1), a1 + hstepA, voffA);
;             PG8_WAIT_L(8); PG8_BAR; PG8_WAIT_L(0); PG8_MMA(0, 0, At, B0); PG8_BAR; PG8_SCHED;
;             PG8_LDB(B1, 0, 1); PG8_STAGE(PG8_SB(0, 0), b2, voffB);
;             PG8_BAR; PG8_WAIT_L(0); PG8_MMA(0, 1, At, B1); PG8_BAR;
;             PG8_LDA(At, 0, 1); PG8_STAGE(PG8_SA(0, 0), a2, voffA);
;             PG8_BAR; PG8_WAIT_L(0); PG8_MMA(1, 0, At, B0); PG8_BAR; PG8_SCHED;
;             PG8_STAGE(PG8_SB(0, 1), b2 + hstepB, voffB);
;             PG8_WAIT_V(6); PG8_BAR; PG8_MMA(1, 1, At, B1); PG8_BAR;
.Lp7_prio_done:
.LBB0_1209:
	ds_read_b128 v[152:155], v147
	ds_read_b128 v[156:159], v147 offset:1024
	ds_read_b128 v[160:163], v147 offset:2048
	ds_read_b128 v[164:167], v147 offset:3072
	s_add_u32 s26, s24, 0xfff80080
	s_addc_u32 s27, s25, -1
	s_cmp_eq_u32 s45, 28
	s_cselect_b32 s37, s4, s27
	s_cselect_b32 s36, s5, s26
	s_cselect_b32 s27, s9, s44
	s_cselect_b32 s26, s11, s43
	v_lshl_add_u64 v[202:203], s[24:25], 0, v[136:137]
	s_add_i32 m0, s19, 0xc000
	ds_read_b128 v[168:171], v148
	ds_read_b128 v[172:175], v148 offset:1024
	ds_read_b128 v[176:179], v148 offset:2048
	ds_read_b128 v[180:183], v148 offset:3072
	ds_read_b128 v[184:187], v148 offset:4096
	ds_read_b128 v[188:191], v148 offset:5120
	ds_read_b128 v[192:195], v148 offset:6144
	ds_read_b128 v[198:201], v148 offset:7168
	global_load_lds_dwordx4 v[202:203], off
	v_lshl_add_u64 v[202:203], s[24:25], 0, v[138:139]
	s_add_i32 m0, s19, 0xe000
	s_nop 0
	global_load_lds_dwordx4 v[202:203], off
	s_waitcnt lgkmcnt(8)
	s_barrier
	s_waitcnt lgkmcnt(0)
	s_waitcnt lgkmcnt(0)
	v_mfma_f32_16x16x32_bf16 v[116:119], v[152:155], v[168:171], v[116:119]
	v_mfma_f32_16x16x32_bf16 v[112:115], v[160:163], v[168:171], v[112:115]
	v_mfma_f32_16x16x32_bf16 v[108:111], v[152:155], v[176:179], v[108:111]
	v_mfma_f32_16x16x32_bf16 v[100:103], v[160:163], v[176:179], v[100:103]
	v_mfma_f32_16x16x32_bf16 v[92:95], v[152:155], v[184:187], v[92:95]
	v_mfma_f32_16x16x32_bf16 v[84:87], v[160:163], v[184:187], v[84:87]
	v_mfma_f32_16x16x32_bf16 v[76:79], v[152:155], v[192:195], v[76:79]
	v_mfma_f32_16x16x32_bf16 v[68:71], v[160:163], v[192:195], v[68:71]
	v_mfma_f32_16x16x32_bf16 v[116:119], v[156:159], v[172:175], v[116:119]
	v_mfma_f32_16x16x32_bf16 v[112:115], v[164:167], v[172:175], v[112:115]
	v_mfma_f32_16x16x32_bf16 v[108:111], v[156:159], v[180:183], v[108:111]
	v_mfma_f32_16x16x32_bf16 v[100:103], v[164:167], v[180:183], v[100:103]
	v_mfma_f32_16x16x32_bf16 v[92:95], v[156:159], v[188:191], v[92:95]
	v_mfma_f32_16x16x32_bf16 v[84:87], v[164:167], v[188:191], v[84:87]
	v_mfma_f32_16x16x32_bf16 v[76:79], v[156:159], v[198:201], v[76:79]
	v_mfma_f32_16x16x32_bf16 v[68:71], v[164:167], v[198:201], v[68:71]
	s_barrier
	s_add_i32 s50, s38, s22
	v_lshl_add_u64 v[218:219], s[26:27], 0, v[130:131]
	s_mov_b32 m0, s50
	ds_read_b128 v[202:205], v149
	ds_read_b128 v[206:209], v149 offset:1024
	ds_read_b128 v[210:213], v149 offset:2048
	ds_read_b128 v[214:217], v149 offset:3072
	global_load_lds_dwordx4 v[218:219], off
	v_lshl_add_u64 v[220:221], s[26:27], 0, v[134:135]
	s_add_i32 m0, s50, 0x2000
	s_nop 0
	global_load_lds_dwordx4 v[220:221], off
	s_barrier
	s_waitcnt lgkmcnt(0)
	s_waitcnt lgkmcnt(0)
	v_mfma_f32_16x16x32_bf16 v[124:127], v[202:205], v[168:171], v[124:127]
	v_mfma_f32_16x16x32_bf16 v[120:123], v[210:213], v[168:171], v[120:123]
	v_mfma_f32_16x16x32_bf16 v[104:107], v[202:205], v[176:179], v[104:107]
	v_mfma_f32_16x16x32_bf16 v[96:99], v[210:213], v[176:179], v[96:99]
	v_mfma_f32_16x16x32_bf16 v[88:91], v[202:205], v[184:187], v[88:91]
	v_mfma_f32_16x16x32_bf16 v[80:83], v[210:213], v[184:187], v[80:83]
	v_mfma_f32_16x16x32_bf16 v[72:75], v[202:205], v[192:195], v[72:75]
	v_mfma_f32_16x16x32_bf16 v[64:67], v[210:213], v[192:195], v[64:67]
	v_mfma_f32_16x16x32_bf16 v[124:127], v[206:209], v[172:175], v[124:127]
	v_mfma_f32_16x16x32_bf16 v[120:123], v[214:217], v[172:175], v[120:123]
	v_mfma_f32_16x16x32_bf16 v[104:107], v[206:209], v[180:183], v[104:107]
	v_mfma_f32_16x16x32_bf16 v[96:99], v[214:217], v[180:183], v[96:99]
	v_mfma_f32_16x16x32_bf16 v[88:91], v[206:209], v[188:191], v[88:91]
	v_mfma_f32_16x16x32_bf16 v[80:83], v[214:217], v[188:191], v[80:83]
	v_mfma_f32_16x16x32_bf16 v[72:75], v[206:209], v[198:201], v[72:75]
	v_mfma_f32_16x16x32_bf16 v[64:67], v[214:217], v[198:201], v[64:67]
	s_mov_b32 m0, s19
	v_lshl_add_u64 v[222:223], s[36:37], 0, v[128:129]
	s_barrier
	ds_read_b128 v[168:171], v148 offset:16384
	ds_read_b128 v[172:175], v148 offset:17408
	ds_read_b128 v[176:179], v148 offset:18432
	ds_read_b128 v[180:183], v148 offset:19456
	ds_read_b128 v[184:187], v148 offset:20480
	ds_read_b128 v[188:191], v148 offset:21504
	ds_read_b128 v[192:195], v148 offset:22528
	ds_read_b128 v[198:201], v148 offset:23552
	global_load_lds_dwordx4 v[222:223], off
	v_lshl_add_u64 v[224:225], s[36:37], 0, v[132:133]
	s_mov_b32 m0, s23
	s_nop 0
	global_load_lds_dwordx4 v[224:225], off
	s_barrier
	s_waitcnt lgkmcnt(0)
	s_waitcnt lgkmcnt(0)
	v_mfma_f32_16x16x32_bf16 v[60:63], v[152:155], v[168:171], v[60:63]
	v_mfma_f32_16x16x32_bf16 v[52:55], v[160:163], v[168:171], v[52:55]
	v_mfma_f32_16x16x32_bf16 v[44:47], v[152:155], v[176:179], v[44:47]
	v_mfma_f32_16x16x32_bf16 v[36:39], v[160:163], v[176:179], v[36:39]
	v_mfma_f32_16x16x32_bf16 v[28:31], v[152:155], v[184:187], v[28:31]
	v_mfma_f32_16x16x32_bf16 v[20:23], v[160:163], v[184:187], v[20:23]
	v_mfma_f32_16x16x32_bf16 v[12:15], v[152:155], v[192:195], v[12:15]
	v_mfma_f32_16x16x32_bf16 v[4:7], v[160:163], v[192:195], v[4:7]
	v_mfma_f32_16x16x32_bf16 v[60:63], v[156:159], v[172:175], v[60:63]
	v_mfma_f32_16x16x32_bf16 v[52:55], v[164:167], v[172:175], v[52:55]
	v_mfma_f32_16x16x32_bf16 v[44:47], v[156:159], v[180:183], v[44:47]
	v_mfma_f32_16x16x32_bf16 v[36:39], v[164:167], v[180:183], v[36:39]
	v_mfma_f32_16x16x32_bf16 v[28:31], v[156:159], v[188:191], v[28:31]
	v_mfma_f32_16x16x32_bf16 v[20:23], v[164:167], v[188:191], v[20:23]
	v_mfma_f32_16x16x32_bf16 v[12:15], v[156:159], v[198:201], v[12:15]
	v_mfma_f32_16x16x32_bf16 v[4:7], v[164:167], v[198:201], v[4:7]
	s_barrier
; #define PG8_STAGE(bufoff, gbase, voff) do { _Pragma("unroll") for (int _i = 0; _i < 2; ++_i) \
;         __builtin_amdgcn_global_load_lds((const unsigned*)((const char*)(gbase) + (voff)[_i]), (LAS unsigned*)(lds + (bufoff) + ldsw + _i * 8192), 16, 0, 0); } while (0)
; #define PG8_LDA(dst, b, h) do { _Pragma("unroll") for (int m = 0; m < 4; ++m) _Pragma("unroll") for (int k = 0; k < 2; ++k) dst[m][k] = *(const LAS bf16x8*)(lds + PG8_SA(b, h) + aoff + m * 2048 + k * 1024); } while (0)
; #define PG8_LDB(dst, b, h) do { _Pragma("unroll") for (int n = 0; n < 2; ++n) _Pragma("unroll") for (int k = 0; k < 2; ++k) dst[n][k] = *(const LAS bf16x8*)(lds + PG8_SB(b, h) + boff + n * 2048 + k * 1024); } while (0)
; #define PG8_MMA(ai, bj, At, Bt) do { __builtin_amdgcn_s_setprio(1); _Pragma("unroll") for (int m = 0; m < 4; ++m) _Pragma("unroll") for (int n = 0; n < 2; ++n) _Pragma("unroll") for (int k = 0; k < 2; ++k) \
;         acc[ai][bj][m][n] = __builtin_amdgcn_mfma_f32_16x16x32_bf16(Bt[n][k], At[m][k], acc[ai][bj][m][n], 0, 0, 0); __builtin_amdgcn_s_setprio(0); } while (0)
; #define PG8_WAIT_V(n) asm volatile("s_waitcnt vmcnt(" #n ")" ::: "memory")
; #define PG8_WAIT_L(n) asm volatile("s_waitcnt lgkmcnt(" #n ")" ::: "memory")
; #define PG8_BAR __builtin_amdgcn_s_barrier()
; #define PG8_SCHED __builtin_amdgcn_sched_barrier(0)
; template <class Epi, class Sched>
; __device__ __forceinline__ void gemm_phase(LAS unsigned char* lds, const Gemm g, const Sched& S, const Epi& E) {
;     ...
;             PG8_STAGE(PG8_SB(0, 1), b2 + hstepB, voffB);
;             PG8_WAIT_V(6); PG8_BAR; PG8_MMA(1, 1, At, B1); PG8_BAR;
;             PG8_LDB(B0, 1, 0); PG8_SCHED; PG8_LDA(At, 1, 0); PG8_STAGE(PG8_SA(0, 1), a2 + hstepA, voffA);
;             PG8_WAIT_L(8); PG8_BAR; PG8_WAIT_L(0); PG8_MMA(0, 0, At, B0); PG8_BAR; PG8_SCHED;
;             PG8_LDB(B1, 1, 1); PG8_STAGE(PG8_SB(1, 0), b3, voffB);
;             PG8_BAR; PG8_WAIT_L(0); PG8_MMA(0, 1, At, B1); PG8_BAR;
;             PG8_LDA(At, 1, 1); PG8_STAGE(PG8_SA(1, 0), a3, voffA);
;             PG8_BAR; PG8_WAIT_L(0); PG8_MMA(1, 0, At, B0); PG8_BAR; PG8_SCHED;
;             PG8_STAGE(PG8_SB(1, 1), b3 + hstepB, voffB);
;             PG8_WAIT_V(6); PG8_BAR; PG8_MMA(1, 1, At, B1); PG8_BAR;
	s_add_u32 s50, s26, 0x80000
	s_addc_u32 s51, s27, 0
	s_add_i32 s52, s39, s22
	v_lshl_add_u64 v[152:153], s[50:51], 0, v[130:131]
	s_mov_b32 m0, s52
	s_nop 0
	global_load_lds_dwordx4 v[152:153], off
	v_lshl_add_u64 v[152:153], s[50:51], 0, v[134:135]
	s_add_i32 m0, s52, 0x2000
	s_nop 0
	global_load_lds_dwordx4 v[152:153], off
	s_waitcnt vmcnt(6)
	s_barrier
	v_mfma_f32_16x16x32_bf16 v[56:59], v[202:205], v[168:171], v[56:59]
	v_mfma_f32_16x16x32_bf16 v[48:51], v[210:213], v[168:171], v[48:51]
	v_mfma_f32_16x16x32_bf16 v[40:43], v[202:205], v[176:179], v[40:43]
	v_mfma_f32_16x16x32_bf16 v[32:35], v[210:213], v[176:179], v[32:35]
	v_mfma_f32_16x16x32_bf16 v[24:27], v[202:205], v[184:187], v[24:27]
	v_mfma_f32_16x16x32_bf16 v[16:19], v[210:213], v[184:187], v[16:19]
	v_mfma_f32_16x16x32_bf16 v[8:11], v[202:205], v[192:195], v[8:11]
	v_mfma_f32_16x16x32_bf16 v[0:3], v[210:213], v[192:195], v[0:3]
	v_mfma_f32_16x16x32_bf16 v[56:59], v[206:209], v[172:175], v[56:59]
	v_mfma_f32_16x16x32_bf16 v[48:51], v[214:217], v[172:175], v[48:51]
	v_mfma_f32_16x16x32_bf16 v[40:43], v[206:209], v[180:183], v[40:43]
	v_mfma_f32_16x16x32_bf16 v[32:35], v[214:217], v[180:183], v[32:35]
	v_mfma_f32_16x16x32_bf16 v[24:27], v[206:209], v[188:191], v[24:27]
	v_mfma_f32_16x16x32_bf16 v[16:19], v[214:217], v[188:191], v[16:19]
	v_mfma_f32_16x16x32_bf16 v[8:11], v[206:209], v[198:201], v[8:11]
	v_mfma_f32_16x16x32_bf16 v[0:3], v[214:217], v[198:201], v[0:3]
	s_add_i32 s50, 0, 0x18000
	v_add_u32_e32 v151, s50, v145
	s_barrier
	ds_read_b128 v[152:155], v151
	ds_read_b128 v[156:159], v151 offset:1024
	ds_read_b128 v[160:163], v151 offset:2048
	ds_read_b128 v[164:167], v151 offset:3072
	s_add_u32 s36, s36, 0x80000
	s_addc_u32 s37, s37, 0
	s_mov_b32 m0, s29
	v_lshl_add_u64 v[202:203], s[36:37], 0, v[128:129]
	ds_read_b128 v[168:171], v148 offset:32768
	ds_read_b128 v[172:175], v148 offset:33792
	ds_read_b128 v[176:179], v148 offset:34816
	ds_read_b128 v[180:183], v148 offset:35840
	ds_read_b128 v[184:187], v148 offset:36864
	ds_read_b128 v[188:191], v148 offset:37888
	ds_read_b128 v[192:195], v148 offset:38912
	ds_read_b128 v[198:201], v148 offset:39936
	global_load_lds_dwordx4 v[202:203], off
	v_lshl_add_u64 v[202:203], s[36:37], 0, v[132:133]
	s_mov_b32 m0, s30
	s_nop 0
	global_load_lds_dwordx4 v[202:203], off
	s_waitcnt lgkmcnt(8)
	s_barrier
	s_waitcnt lgkmcnt(0)
	s_waitcnt lgkmcnt(0)
	v_mfma_f32_16x16x32_bf16 v[116:119], v[152:155], v[168:171], v[116:119]
	v_mfma_f32_16x16x32_bf16 v[112:115], v[160:163], v[168:171], v[112:115]
	v_mfma_f32_16x16x32_bf16 v[108:111], v[152:155], v[176:179], v[108:111]
	v_mfma_f32_16x16x32_bf16 v[100:103], v[160:163], v[176:179], v[100:103]
	v_mfma_f32_16x16x32_bf16 v[92:95], v[152:155], v[184:187], v[92:95]
	v_mfma_f32_16x16x32_bf16 v[84:87], v[160:163], v[184:187], v[84:87]
	v_mfma_f32_16x16x32_bf16 v[76:79], v[152:155], v[192:195], v[76:79]
	v_mfma_f32_16x16x32_bf16 v[68:71], v[160:163], v[192:195], v[68:71]
	v_mfma_f32_16x16x32_bf16 v[116:119], v[156:159], v[172:175], v[116:119]
	v_mfma_f32_16x16x32_bf16 v[112:115], v[164:167], v[172:175], v[112:115]
	v_mfma_f32_16x16x32_bf16 v[108:111], v[156:159], v[180:183], v[108:111]
	v_mfma_f32_16x16x32_bf16 v[100:103], v[164:167], v[180:183], v[100:103]
	v_mfma_f32_16x16x32_bf16 v[92:95], v[156:159], v[188:191], v[92:95]
	v_mfma_f32_16x16x32_bf16 v[84:87], v[164:167], v[188:191], v[84:87]
	v_mfma_f32_16x16x32_bf16 v[76:79], v[156:159], v[198:201], v[76:79]
	v_mfma_f32_16x16x32_bf16 v[68:71], v[164:167], v[198:201], v[68:71]
	s_barrier
	s_add_i32 s36, 0, 0x1c000
	s_add_i32 s37, s50, s22
	v_add_u32_e32 v151, s36, v145
	v_lshl_add_u64 v[218:219], v[218:219], 0, s[6:7]
	s_mov_b32 m0, s37
	ds_read_b128 v[202:205], v151
	ds_read_b128 v[206:209], v151 offset:1024
	ds_read_b128 v[210:213], v151 offset:2048
	ds_read_b128 v[214:217], v151 offset:3072
	global_load_lds_dwordx4 v[218:219], off
	v_lshl_add_u64 v[218:219], v[220:221], 0, s[6:7]
	s_add_i32 m0, s37, 0x2000
	s_nop 0
	global_load_lds_dwordx4 v[218:219], off
	s_barrier
	s_waitcnt lgkmcnt(0)
	s_waitcnt lgkmcnt(0)
	v_mfma_f32_16x16x32_bf16 v[124:127], v[202:205], v[168:171], v[124:127]
	v_mfma_f32_16x16x32_bf16 v[120:123], v[210:213], v[168:171], v[120:123]
	v_mfma_f32_16x16x32_bf16 v[104:107], v[202:205], v[176:179], v[104:107]
	v_mfma_f32_16x16x32_bf16 v[96:99], v[210:213], v[176:179], v[96:99]
	v_mfma_f32_16x16x32_bf16 v[88:91], v[202:205], v[184:187], v[88:91]
	v_mfma_f32_16x16x32_bf16 v[80:83], v[210:213], v[184:187], v[80:83]
	v_mfma_f32_16x16x32_bf16 v[72:75], v[202:205], v[192:195], v[72:75]
	v_mfma_f32_16x16x32_bf16 v[64:67], v[210:213], v[192:195], v[64:67]
	v_mfma_f32_16x16x32_bf16 v[124:127], v[206:209], v[172:175], v[124:127]
	v_mfma_f32_16x16x32_bf16 v[120:123], v[214:217], v[172:175], v[120:123]
	v_mfma_f32_16x16x32_bf16 v[104:107], v[206:209], v[180:183], v[104:107]
	v_mfma_f32_16x16x32_bf16 v[96:99], v[214:217], v[180:183], v[96:99]
	v_mfma_f32_16x16x32_bf16 v[88:91], v[206:209], v[188:191], v[88:91]
	v_mfma_f32_16x16x32_bf16 v[80:83], v[214:217], v[188:191], v[80:83]
	v_mfma_f32_16x16x32_bf16 v[72:75], v[206:209], v[198:201], v[72:75]
	v_mfma_f32_16x16x32_bf16 v[64:67], v[214:217], v[198:201], v[64:67]
	s_mov_b32 m0, s33
	v_lshl_add_u64 v[218:219], v[222:223], 0, s[6:7]
	s_barrier
	ds_read_b128 v[168:171], v148 offset:49152
	ds_read_b128 v[172:175], v148 offset:50176
	ds_read_b128 v[176:179], v148 offset:51200
	ds_read_b128 v[180:183], v148 offset:52224
	ds_read_b128 v[184:187], v148 offset:53248
	ds_read_b128 v[188:191], v148 offset:54272
	ds_read_b128 v[192:195], v148 offset:55296
	ds_read_b128 v[198:201], v148 offset:56320
	global_load_lds_dwordx4 v[218:219], off
	v_lshl_add_u64 v[218:219], v[224:225], 0, s[6:7]
	s_mov_b32 m0, s34
	s_nop 0
	global_load_lds_dwordx4 v[218:219], off
	s_barrier
; __device__ __forceinline__ unsigned pk_bf16(float lo, float hi) { unsigned r; asm volatile("v_cvt_pk_bf16_f32 %0, %1, %2" : "=v"(r) : "v"(lo), "v"(hi)); return r; }
; __device__ __forceinline__ float sigmoidf_(float x) { return __builtin_amdgcn_rcpf(1.0f + __expf(-x)); }
; #define PG8_STAGE(bufoff, gbase, voff) do { _Pragma("unroll") for (int _i = 0; _i < 2; ++_i) \
;         __builtin_amdgcn_global_load_lds((const unsigned*)((const char*)(gbase) + (voff)[_i]), (LAS unsigned*)(lds + (bufoff) + ldsw + _i * 8192), 16, 0, 0); } while (0)
; #define PG8_WAIT_V(n) asm volatile("s_waitcnt vmcnt(" #n ")" ::: "memory")
; #define PG8_WAIT_L(n) asm volatile("s_waitcnt lgkmcnt(" #n ")" ::: "memory")
; #define PG8_BAR __builtin_amdgcn_s_barrier()
; template <class Epi, class Sched>
; __device__ __forceinline__ void gemm_phase(LAS unsigned char* lds, const Gemm g, const Sched& S, const Epi& E) {
;     ...
;             PG8_BAR; PG8_WAIT_L(0); PG8_MMA(1, 0, At, B0); PG8_BAR; PG8_SCHED;
;             PG8_STAGE(PG8_SB(1, 1), b3 + hstepB, voffB);
;             PG8_WAIT_V(6); PG8_BAR; PG8_MMA(1, 1, At, B1); PG8_BAR;
;         }
;         if constexpr (!Epi::AFTER_DRAIN) E(acc, cur, wr, wc, fr, fq);
;     __device__ __forceinline__ void operator()(const f32x4 (&acc)[2][2][4][2], const Unit& u, int wr, int wc, int fr, int fq) const {
;         const int row0 = u.pm * 256 + wr * 64 + fr, col0 = u.pn * 128 + wc * 32 + 8 * fq;
;         float rs[2][4];
; #pragma unroll
;         for (int ai = 0; ai < 2; ++ai)
; #pragma unroll
;             for (int m = 0; m < 4; ++m) rs[ai][m] = rowsq[row0 + ai * 128 + m * 16];
; #pragma unroll
;         for (int ai = 0; ai < 2; ++ai)
; #pragma unroll
;             for (int m = 0; m < 4; ++m) {
;                 const int row = row0 + ai * 128 + m * 16;
;                 const float rstd = rsqrtf(rs[ai][m] * (1.0f / D) + RMS_EPS);
;                 f32x4 o[2];
; #pragma unroll
;                 for (int n = 0; n < 2; ++n)
; #pragma unroll
;                     for (int j = 0; j < 4; ++j) { const float gt = acc[ai][0][m][n][j] * rstd, up = acc[ai][1][m][n][j] * rstd; o[n][j] = gt * sigmoidf_(gt) * up; }
;                 u32x4 w; w.x = pk_bf16(o[0][0], o[0][1]); w.y = pk_bf16(o[0][2], o[0][3]); w.z = pk_bf16(o[1][0], o[1][1]); w.w = pk_bf16(o[1][2], o[1][3]);
;                 *(u32x4*)(U + (size_t)row * DFF + col0) = w;
	s_waitcnt lgkmcnt(0)
	s_waitcnt lgkmcnt(0)
	v_mfma_f32_16x16x32_bf16 v[60:63], v[152:155], v[168:171], v[60:63]
	v_mfma_f32_16x16x32_bf16 v[52:55], v[160:163], v[168:171], v[52:55]
	v_mfma_f32_16x16x32_bf16 v[44:47], v[152:155], v[176:179], v[44:47]
	v_mfma_f32_16x16x32_bf16 v[36:39], v[160:163], v[176:179], v[36:39]
	v_mfma_f32_16x16x32_bf16 v[28:31], v[152:155], v[184:187], v[28:31]
	v_mfma_f32_16x16x32_bf16 v[20:23], v[160:163], v[184:187], v[20:23]
	v_mfma_f32_16x16x32_bf16 v[12:15], v[152:155], v[192:195], v[12:15]
	v_mfma_f32_16x16x32_bf16 v[4:7], v[160:163], v[192:195], v[4:7]
	v_mfma_f32_16x16x32_bf16 v[60:63], v[156:159], v[172:175], v[60:63]
	v_mfma_f32_16x16x32_bf16 v[52:55], v[164:167], v[172:175], v[52:55]
	v_mfma_f32_16x16x32_bf16 v[44:47], v[156:159], v[180:183], v[44:47]
	v_mfma_f32_16x16x32_bf16 v[36:39], v[164:167], v[180:183], v[36:39]
	v_mfma_f32_16x16x32_bf16 v[28:31], v[156:159], v[188:191], v[28:31]
	v_mfma_f32_16x16x32_bf16 v[20:23], v[164:167], v[188:191], v[20:23]
	v_mfma_f32_16x16x32_bf16 v[12:15], v[156:159], v[198:201], v[12:15]
	v_mfma_f32_16x16x32_bf16 v[4:7], v[164:167], v[198:201], v[4:7]
	s_barrier
	s_add_u32 s26, s26, 0x80080
	s_addc_u32 s27, s27, 0
	s_add_i32 s36, s36, s22
	v_lshl_add_u64 v[152:153], s[26:27], 0, v[130:131]
	s_mov_b32 m0, s36
	s_nop 0
	global_load_lds_dwordx4 v[152:153], off
	v_lshl_add_u64 v[152:153], s[26:27], 0, v[134:135]
	s_add_i32 m0, s36, 0x2000
	s_nop 0
	global_load_lds_dwordx4 v[152:153], off
	s_waitcnt vmcnt(6)
	s_barrier
	v_mfma_f32_16x16x32_bf16 v[56:59], v[202:205], v[168:171], v[56:59]
	v_mfma_f32_16x16x32_bf16 v[48:51], v[210:213], v[168:171], v[48:51]
	v_mfma_f32_16x16x32_bf16 v[40:43], v[202:205], v[176:179], v[40:43]
	v_mfma_f32_16x16x32_bf16 v[32:35], v[210:213], v[176:179], v[32:35]
	v_mfma_f32_16x16x32_bf16 v[24:27], v[202:205], v[184:187], v[24:27]
	v_mfma_f32_16x16x32_bf16 v[16:19], v[210:213], v[184:187], v[16:19]
	v_mfma_f32_16x16x32_bf16 v[8:11], v[202:205], v[192:195], v[8:11]
	v_mfma_f32_16x16x32_bf16 v[0:3], v[210:213], v[192:195], v[0:3]
	v_mfma_f32_16x16x32_bf16 v[56:59], v[206:209], v[172:175], v[56:59]
	v_mfma_f32_16x16x32_bf16 v[48:51], v[214:217], v[172:175], v[48:51]
	v_mfma_f32_16x16x32_bf16 v[40:43], v[206:209], v[180:183], v[40:43]
	v_mfma_f32_16x16x32_bf16 v[32:35], v[214:217], v[180:183], v[32:35]
	v_mfma_f32_16x16x32_bf16 v[24:27], v[206:209], v[188:191], v[24:27]
	v_mfma_f32_16x16x32_bf16 v[16:19], v[214:217], v[188:191], v[16:19]
	v_mfma_f32_16x16x32_bf16 v[8:11], v[206:209], v[198:201], v[8:11]
	v_mfma_f32_16x16x32_bf16 v[0:3], v[214:217], v[198:201], v[0:3]
	s_add_i32 s45, s45, 2
	s_add_u32 s24, s24, 0x100
	s_addc_u32 s25, s25, 0
	s_add_u32 s43, s43, 0x100
	s_addc_u32 s44, s44, 0
	s_cmp_gt_u32 s45, 29
	s_barrier
	s_cbranch_scc0 .LBB0_1209
	s_setprio 0
	v_lshl_add_u32 v154, s18, 8, v144
	v_ashrrev_i32_e32 v155, 31, v154
	v_lshl_add_u64 v[156:157], v[154:155], 2, s[96:97]
	v_mov_b32_e32 v155, v228
	v_or_b32_e32 v168, 16, v154
	v_ashrrev_i32_e32 v169, 31, v168
	v_lshl_add_u64 v[170:171], v[168:169], 2, s[96:97]
	v_mov_b32_e32 v169, v229
	v_mov_b32_e32 v166, v122
	v_or_b32_e32 v122, 48, v154
	v_mov_b32_e32 v160, v124
	v_mov_b32_e32 v167, v114
	v_mov_b32_e32 v114, v123
	v_or_b32_e32 v124, 32, v154
	v_ashrrev_i32_e32 v123, 31, v122
	v_mov_b32_e32 v161, v116
	v_mov_b32_e32 v116, v125
	v_ashrrev_i32_e32 v125, 31, v124
	v_lshl_add_u64 v[172:173], v[122:123], 2, s[96:97]
	v_lshl_add_u64 v[170:171], v[124:125], 2, s[96:97]
	v_mov_b32_e32 v162, v126
	v_mov_b32_e32 v174, v232
	v_mov_b32_e32 v153, v233
	v_mov_b32_e32 v151, v197
	s_nop 0
	v_mov_b32_e32 v170, v230
	s_nop 0
	v_mov_b32_e32 v171, v231
	v_mov_b32_e32 v126, v226
	v_mov_b32_e32 v165, v112
	v_mov_b32_e32 v112, v121
	v_mov_b32_e32 v163, v118
	v_mov_b32_e32 v118, v127
	v_mov_b32_e32 v164, v120
	v_mov_b64_e32 v[120:121], s[48:49]
	v_add_u32_e32 v152, 0x80, v154
	v_add_u32_e32 v127, 0x90, v154
	v_lshl_or_b32 v158, s42, 7, v146
	v_ashrrev_i32_e32 v159, 31, v158
	s_mov_b32 s42, s8
	s_mov_b32 s18, s10
	s_mov_b64 s[26:27], s[16:17]
	s_mov_b64 s[24:25], s[12:13]
	s_waitcnt vmcnt(6)
	v_fmamk_f32 v123, v155, 0x3a000000, v150
	v_mul_f32_e32 v125, 0x4b800000, v123
	v_cmp_gt_f32_e32 vcc, s40, v123
	s_nop 1
	v_cndmask_b32_e32 v123, v123, v125, vcc
	v_rsq_f32_e32 v155, v123
	v_add_u32_e32 v125, 0xa0, v154
	v_add_u32_e32 v123, 0xb0, v154
	v_mul_f32_e32 v156, 0x45800000, v155
	v_cndmask_b32_e32 v156, v155, v156, vcc
	v_pk_mul_f32 v[116:117], v[116:117], v[156:157] op_sel_hi:[1,0]
	v_pk_mul_f32 v[112:113], v[112:113], v[156:157] op_sel_hi:[1,0]
	v_pk_mul_f32 v[160:161], v[160:161], v[156:157] op_sel_hi:[1,0]
	v_pk_mul_f32 v[162:163], v[162:163], v[156:157] op_sel_hi:[1,0]
	v_pk_mul_f32 v[118:119], v[118:119], v[156:157] op_sel_hi:[1,0]
	v_pk_mul_f32 v[164:165], v[164:165], v[156:157] op_sel_hi:[1,0]
	v_pk_mul_f32 v[166:167], v[166:167], v[156:157] op_sel_hi:[1,0]
	v_pk_mul_f32 v[114:115], v[114:115], v[156:157] op_sel_hi:[1,0]
	v_mul_f32_e32 v156, 0xbfb8aa3b, v117
	v_mul_f32_e32 v175, 0xbfb8aa3b, v113
	v_mul_f32_e32 v155, 0xbfb8aa3b, v161
	v_mul_f32_e32 v157, 0xbfb8aa3b, v163
	v_mul_f32_e32 v172, 0xbfb8aa3b, v119
	v_mul_f32_e32 v173, 0xbfb8aa3b, v165
	v_mul_f32_e32 v176, 0xbfb8aa3b, v167
	v_mul_f32_e32 v177, 0xbfb8aa3b, v115
	v_exp_f32_e32 v156, v156
	v_exp_f32_e32 v175, v175
	v_exp_f32_e32 v155, v155
	v_exp_f32_e32 v157, v157
	v_exp_f32_e32 v172, v172
	v_exp_f32_e32 v173, v173
	v_exp_f32_e32 v176, v176
	v_exp_f32_e32 v177, v177
	v_add_f32_e32 v156, 1.0, v156
	v_add_f32_e32 v175, 1.0, v175
	v_add_f32_e32 v155, 1.0, v155
	v_add_f32_e32 v157, 1.0, v157
	v_add_f32_e32 v172, 1.0, v172
	v_add_f32_e32 v173, 1.0, v173
; __device__ __forceinline__ unsigned pk_bf16(float lo, float hi) { unsigned r; asm volatile("v_cvt_pk_bf16_f32 %0, %1, %2" : "=v"(r) : "v"(lo), "v"(hi)); return r; }
; __device__ __forceinline__ float sigmoidf_(float x) { return __builtin_amdgcn_rcpf(1.0f + __expf(-x)); }
;     __device__ __forceinline__ void operator()(const f32x4 (&acc)[2][2][4][2], const Unit& u, int wr, int wc, int fr, int fq) const {
;     ...
;             for (int m = 0; m < 4; ++m) rs[ai][m] = rowsq[row0 + ai * 128 + m * 16];
; #pragma unroll
;         for (int ai = 0; ai < 2; ++ai)
; #pragma unroll
;             for (int m = 0; m < 4; ++m) {
;                 const int row = row0 + ai * 128 + m * 16;
;                 const float rstd = rsqrtf(rs[ai][m] * (1.0f / D) + RMS_EPS);
;                 f32x4 o[2];
; #pragma unroll
;                 for (int n = 0; n < 2; ++n)
; #pragma unroll
;                     for (int j = 0; j < 4; ++j) { const float gt = acc[ai][0][m][n][j] * rstd, up = acc[ai][1][m][n][j] * rstd; o[n][j] = gt * sigmoidf_(gt) * up; }
;                 u32x4 w; w.x = pk_bf16(o[0][0], o[0][1]); w.y = pk_bf16(o[0][2], o[0][3]); w.z = pk_bf16(o[1][0], o[1][1]); w.w = pk_bf16(o[1][2], o[1][3]);
;                 *(u32x4*)(U + (size_t)row * DFF + col0) = w;
	v_add_f32_e32 v176, 1.0, v176
	v_add_f32_e32 v177, 1.0, v177
	v_rcp_f32_e32 v156, v156
	v_rcp_f32_e32 v175, v175
	v_rcp_f32_e32 v155, v155
	v_rcp_f32_e32 v157, v157
	v_rcp_f32_e32 v172, v172
	v_rcp_f32_e32 v173, v173
	v_rcp_f32_e32 v176, v176
	v_rcp_f32_e32 v177, v177
	v_mul_f32_e32 v117, v117, v156
	v_mul_f32_e32 v113, v113, v175
	v_mul_f32_e32 v155, v161, v155
	v_mul_f32_e32 v156, v163, v157
	v_mul_f32_e32 v119, v119, v172
	v_mul_f32_e32 v157, v165, v173
	v_mul_f32_e32 v161, v167, v176
	v_mul_f32_e32 v115, v115, v177
	v_mul_f32_e32 v116, v116, v117
	v_mul_f32_e32 v112, v112, v113
	v_mul_f32_e32 v155, v160, v155
	v_mul_f32_e32 v117, v162, v156
	v_mul_f32_e32 v118, v118, v119
	v_mul_f32_e32 v119, v164, v157
	v_mul_f32_e32 v113, v166, v161
	v_mul_f32_e32 v156, v114, v115
	v_cvt_pk_bf16_f32 v114, v155, v116
	v_cvt_pk_bf16_f32 v115, v117, v118
	v_cvt_pk_bf16_f32 v116, v119, v112
	v_fmamk_f32 v112, v169, 0x3a000000, v150
	v_cvt_pk_bf16_f32 v117, v113, v156
	v_mul_f32_e32 v113, 0x4b800000, v112
	v_cmp_gt_f32_e32 vcc, s40, v112
	v_mad_i64_i32 v[118:119], s[4:5], v154, s41, v[120:121]
	s_nop 0
	v_cndmask_b32_e32 v112, v112, v113, vcc
	v_rsq_f32_e32 v155, v112
	v_mov_b32_e32 v156, v104
	v_mov_b32_e32 v157, v108
	v_mov_b32_e32 v108, v105
	v_mul_f32_e32 v154, 0x45800000, v155
	v_cndmask_b32_e32 v154, v155, v154, vcc
	v_pk_mul_f32 v[156:157], v[156:157], v[154:155] op_sel_hi:[1,0]
	v_lshlrev_b64 v[112:113], 1, v[158:159]
	v_mul_f32_e32 v104, 0xbfb8aa3b, v157
	v_exp_f32_e32 v155, v104
	s_nop 0
	v_pk_mul_f32 v[104:105], v[108:109], v[154:155] op_sel_hi:[1,0]
	s_nop 0
	v_mul_f32_e32 v108, 0xbfb8aa3b, v105
	v_exp_f32_e32 v158, v108
	v_lshl_add_u64 v[108:109], v[118:119], 0, v[112:113]
	v_add_f32_e32 v118, 1.0, v155
	v_rcp_f32_e32 v118, v118
	global_store_dwordx4 v[108:109], v[114:117], off
	v_mov_b32_e32 v109, v110
	v_add_f32_e32 v119, 1.0, v158
	v_mul_f32_e32 v108, v157, v118
	v_mul_f32_e32 v114, v156, v108
	v_mov_b32_e32 v108, v106
	v_pk_mul_f32 v[108:109], v[108:109], v[154:155] op_sel_hi:[1,0]
	v_mov_b32_e32 v110, v107
	v_mul_f32_e32 v106, 0xbfb8aa3b, v109
	v_rcp_f32_e32 v119, v119
	v_exp_f32_e32 v115, v106
	v_pk_mul_f32 v[106:107], v[110:111], v[154:155] op_sel_hi:[1,0]
	v_mul_f32_e32 v105, v105, v119
	v_mul_f32_e32 v110, 0xbfb8aa3b, v107
	v_exp_f32_e32 v110, v110
	v_mul_f32_e32 v111, v104, v105
	v_add_f32_e32 v104, 1.0, v115
	v_rcp_f32_e32 v115, v104
	v_add_f32_e32 v104, 1.0, v110
	v_rcp_f32_e32 v110, v104
	v_mov_b32_e32 v104, v96
	v_mov_b32_e32 v105, v100
	v_pk_mul_f32 v[104:105], v[104:105], v[154:155] op_sel_hi:[1,0]
	v_mul_f32_e32 v100, v109, v115
	v_mul_f32_e32 v96, 0xbfb8aa3b, v105
	v_exp_f32_e32 v96, v96
	v_mul_f32_e32 v108, v108, v100
	v_mov_b32_e32 v100, v97
	v_mul_f32_e32 v107, v107, v110
	v_add_f32_e32 v96, 1.0, v96
	v_rcp_f32_e32 v109, v96
	v_pk_mul_f32 v[96:97], v[100:101], v[154:155] op_sel_hi:[1,0]
	v_mul_f32_e32 v106, v106, v107
	v_mul_f32_e32 v100, 0xbfb8aa3b, v97
	v_exp_f32_e32 v100, v100
	v_mul_f32_e32 v101, v105, v109
	v_mul_f32_e32 v104, v104, v101
	v_mov_b32_e32 v101, v102
	v_add_f32_e32 v100, 1.0, v100
	v_rcp_f32_e32 v105, v100
	v_mov_b32_e32 v100, v98
	v_pk_mul_f32 v[100:101], v[100:101], v[154:155] op_sel_hi:[1,0]
	v_mov_b32_e32 v102, v99
	v_mul_f32_e32 v98, 0xbfb8aa3b, v101
	v_exp_f32_e32 v107, v98
	v_pk_mul_f32 v[98:99], v[102:103], v[154:155] op_sel_hi:[1,0]
	v_mul_f32_e32 v97, v97, v105
	v_mul_f32_e32 v102, 0xbfb8aa3b, v99
	v_exp_f32_e32 v102, v102
	v_add_f32_e32 v103, 1.0, v107
	v_rcp_f32_e32 v103, v103
	v_mul_f32_e32 v105, v96, v97
	v_add_f32_e32 v102, 1.0, v102
	v_rcp_f32_e32 v102, v102
	v_mul_f32_e32 v96, v101, v103
	v_fmamk_f32 v101, v170, 0x3a000000, v150
	v_mul_f32_e32 v100, v100, v96
	v_mul_f32_e32 v96, v99, v102
	v_mul_f32_e32 v102, 0x4b800000, v101
	v_cmp_gt_f32_e32 vcc, s40, v101
	v_mul_f32_e32 v99, v98, v96
	v_cvt_pk_bf16_f32 v96, v114, v111
	v_cvt_pk_bf16_f32 v97, v108, v106
	v_cvt_pk_bf16_f32 v98, v104, v105
	v_mov_b32_e32 v104, v88
	v_cndmask_b32_e32 v101, v101, v102, vcc
	v_rsq_f32_e32 v102, v101
	v_mov_b32_e32 v105, v92
	v_mov_b32_e32 v92, v89
	v_cvt_pk_bf16_f32 v99, v100, v99
	v_mul_f32_e32 v103, 0x45800000, v102
	v_cndmask_b32_e32 v102, v102, v103, vcc
	v_pk_mul_f32 v[104:105], v[104:105], v[102:103] op_sel_hi:[1,0]
	v_mad_i64_i32 v[100:101], s[4:5], v168, s41, v[120:121]
	v_mul_f32_e32 v88, 0xbfb8aa3b, v105
	v_exp_f32_e32 v103, v88
	s_nop 0
	v_pk_mul_f32 v[88:89], v[92:93], v[102:103] op_sel_hi:[1,0]
	s_nop 0
	v_mul_f32_e32 v92, 0xbfb8aa3b, v89
	v_exp_f32_e32 v106, v92
	v_lshl_add_u64 v[92:93], v[100:101], 0, v[112:113]
	v_add_f32_e32 v100, 1.0, v103
	v_rcp_f32_e32 v100, v100
	global_store_dwordx4 v[92:93], v[96:99], off
	v_mov_b32_e32 v93, v94
	v_add_f32_e32 v101, 1.0, v106
	v_mul_f32_e32 v92, v105, v100
	v_mul_f32_e32 v96, v104, v92
	v_mov_b32_e32 v92, v90
	v_pk_mul_f32 v[92:93], v[92:93], v[102:103] op_sel_hi:[1,0]
	v_mov_b32_e32 v94, v91
	v_mul_f32_e32 v90, 0xbfb8aa3b, v93
	v_rcp_f32_e32 v101, v101
	v_exp_f32_e32 v97, v90
	v_pk_mul_f32 v[90:91], v[94:95], v[102:103] op_sel_hi:[1,0]
	v_mul_f32_e32 v89, v89, v101
	v_mul_f32_e32 v94, 0xbfb8aa3b, v91
	v_exp_f32_e32 v94, v94
	v_mul_f32_e32 v95, v88, v89
	v_add_f32_e32 v88, 1.0, v97
	v_rcp_f32_e32 v97, v88
	v_add_f32_e32 v88, 1.0, v94
	v_rcp_f32_e32 v94, v88
	v_mov_b32_e32 v88, v80
	v_mov_b32_e32 v89, v84
	v_pk_mul_f32 v[88:89], v[88:89], v[102:103] op_sel_hi:[1,0]
	v_mul_f32_e32 v84, v93, v97
	v_mul_f32_e32 v80, 0xbfb8aa3b, v89
	v_exp_f32_e32 v80, v80
	v_mul_f32_e32 v92, v92, v84
	v_mov_b32_e32 v84, v81
	v_mul_f32_e32 v91, v91, v94
	v_add_f32_e32 v80, 1.0, v80
	v_rcp_f32_e32 v93, v80
	v_pk_mul_f32 v[80:81], v[84:85], v[102:103] op_sel_hi:[1,0]
; __device__ __forceinline__ unsigned pk_bf16(float lo, float hi) { unsigned r; asm volatile("v_cvt_pk_bf16_f32 %0, %1, %2" : "=v"(r) : "v"(lo), "v"(hi)); return r; }
; __device__ __forceinline__ float sigmoidf_(float x) { return __builtin_amdgcn_rcpf(1.0f + __expf(-x)); }
;     __device__ __forceinline__ void operator()(const f32x4 (&acc)[2][2][4][2], const Unit& u, int wr, int wc, int fr, int fq) const {
;     ...
;             for (int m = 0; m < 4; ++m) rs[ai][m] = rowsq[row0 + ai * 128 + m * 16];
; #pragma unroll
;         for (int ai = 0; ai < 2; ++ai)
; #pragma unroll
;             for (int m = 0; m < 4; ++m) {
;                 const int row = row0 + ai * 128 + m * 16;
;                 const float rstd = rsqrtf(rs[ai][m] * (1.0f / D) + RMS_EPS);
;                 f32x4 o[2];
; #pragma unroll
;                 for (int n = 0; n < 2; ++n)
; #pragma unroll
;                     for (int j = 0; j < 4; ++j) { const float gt = acc[ai][0][m][n][j] * rstd, up = acc[ai][1][m][n][j] * rstd; o[n][j] = gt * sigmoidf_(gt) * up; }
;                 u32x4 w; w.x = pk_bf16(o[0][0], o[0][1]); w.y = pk_bf16(o[0][2], o[0][3]); w.z = pk_bf16(o[1][0], o[1][1]); w.w = pk_bf16(o[1][2], o[1][3]);
;                 *(u32x4*)(U + (size_t)row * DFF + col0) = w;
	v_mul_f32_e32 v90, v90, v91
	v_mul_f32_e32 v84, 0xbfb8aa3b, v81
	v_exp_f32_e32 v84, v84
	v_mul_f32_e32 v85, v89, v93
	v_mul_f32_e32 v88, v88, v85
	v_mov_b32_e32 v85, v86
	v_add_f32_e32 v84, 1.0, v84
	v_rcp_f32_e32 v89, v84
	v_mov_b32_e32 v84, v82
	v_pk_mul_f32 v[84:85], v[84:85], v[102:103] op_sel_hi:[1,0]
	v_mov_b32_e32 v86, v83
	v_mul_f32_e32 v82, 0xbfb8aa3b, v85
	v_exp_f32_e32 v91, v82
	v_pk_mul_f32 v[82:83], v[86:87], v[102:103] op_sel_hi:[1,0]
	v_mul_f32_e32 v81, v81, v89
	v_mul_f32_e32 v86, 0xbfb8aa3b, v83
	v_exp_f32_e32 v86, v86
	v_add_f32_e32 v87, 1.0, v91
	v_rcp_f32_e32 v87, v87
	v_mul_f32_e32 v89, v80, v81
	v_add_f32_e32 v86, 1.0, v86
	v_rcp_f32_e32 v86, v86
	v_mul_f32_e32 v80, v85, v87
	v_fmamk_f32 v85, v171, 0x3a000000, v150
	v_mul_f32_e32 v84, v84, v80
	v_mul_f32_e32 v80, v83, v86
	v_mul_f32_e32 v86, 0x4b800000, v85
	v_cmp_gt_f32_e32 vcc, s40, v85
	v_mul_f32_e32 v83, v82, v80
	v_cvt_pk_bf16_f32 v80, v96, v95
	v_cvt_pk_bf16_f32 v81, v92, v90
	v_cvt_pk_bf16_f32 v82, v88, v89
	v_mov_b32_e32 v88, v72
	v_cndmask_b32_e32 v85, v85, v86, vcc
	v_rsq_f32_e32 v86, v85
	v_mov_b32_e32 v89, v76
	v_mov_b32_e32 v76, v73
	v_cvt_pk_bf16_f32 v83, v84, v83
	v_mul_f32_e32 v87, 0x45800000, v86
	v_cndmask_b32_e32 v86, v86, v87, vcc
	v_pk_mul_f32 v[88:89], v[88:89], v[86:87] op_sel_hi:[1,0]
	v_mad_i64_i32 v[84:85], s[4:5], v124, s41, v[120:121]
	v_mul_f32_e32 v72, 0xbfb8aa3b, v89
	v_exp_f32_e32 v87, v72
	s_nop 0
	v_pk_mul_f32 v[72:73], v[76:77], v[86:87] op_sel_hi:[1,0]
	s_nop 0
	v_mul_f32_e32 v76, 0xbfb8aa3b, v73
	v_exp_f32_e32 v90, v76
	v_lshl_add_u64 v[76:77], v[84:85], 0, v[112:113]
	v_add_f32_e32 v84, 1.0, v87
	v_rcp_f32_e32 v84, v84
	global_store_dwordx4 v[76:77], v[80:83], off
	v_mov_b32_e32 v77, v78
	v_add_f32_e32 v85, 1.0, v90
	v_mul_f32_e32 v76, v89, v84
	v_mul_f32_e32 v80, v88, v76
	v_mov_b32_e32 v76, v74
	v_pk_mul_f32 v[76:77], v[76:77], v[86:87] op_sel_hi:[1,0]
	v_mov_b32_e32 v78, v75
	v_mul_f32_e32 v74, 0xbfb8aa3b, v77
	v_rcp_f32_e32 v85, v85
	v_exp_f32_e32 v81, v74
	v_pk_mul_f32 v[74:75], v[78:79], v[86:87] op_sel_hi:[1,0]
	v_mul_f32_e32 v73, v73, v85
	v_mul_f32_e32 v78, 0xbfb8aa3b, v75
	v_exp_f32_e32 v78, v78
	v_mul_f32_e32 v79, v72, v73
	v_add_f32_e32 v72, 1.0, v81
	v_rcp_f32_e32 v81, v72
	v_add_f32_e32 v72, 1.0, v78
	v_rcp_f32_e32 v78, v72
	v_mov_b32_e32 v72, v64
	v_mov_b32_e32 v73, v68
	v_pk_mul_f32 v[72:73], v[72:73], v[86:87] op_sel_hi:[1,0]
	v_mul_f32_e32 v68, v77, v81
	v_mul_f32_e32 v64, 0xbfb8aa3b, v73
	v_exp_f32_e32 v64, v64
	v_mul_f32_e32 v76, v76, v68
	v_mov_b32_e32 v68, v65
	v_mul_f32_e32 v75, v75, v78
	v_add_f32_e32 v64, 1.0, v64
	v_rcp_f32_e32 v77, v64
	v_pk_mul_f32 v[64:65], v[68:69], v[86:87] op_sel_hi:[1,0]
	v_mul_f32_e32 v74, v74, v75
	v_mul_f32_e32 v68, 0xbfb8aa3b, v65
	v_exp_f32_e32 v68, v68
	v_mul_f32_e32 v69, v73, v77
	v_mul_f32_e32 v72, v72, v69
	v_mov_b32_e32 v69, v70
	v_add_f32_e32 v68, 1.0, v68
	v_rcp_f32_e32 v73, v68
	v_mov_b32_e32 v68, v66
	v_pk_mul_f32 v[68:69], v[68:69], v[86:87] op_sel_hi:[1,0]
	v_mov_b32_e32 v70, v67
	v_mul_f32_e32 v66, 0xbfb8aa3b, v69
	v_exp_f32_e32 v75, v66
	v_pk_mul_f32 v[66:67], v[70:71], v[86:87] op_sel_hi:[1,0]
	v_mul_f32_e32 v65, v65, v73
	v_mul_f32_e32 v70, 0xbfb8aa3b, v67
	v_exp_f32_e32 v70, v70
	v_add_f32_e32 v71, 1.0, v75
	v_rcp_f32_e32 v71, v71
	v_mul_f32_e32 v73, v64, v65
	v_add_f32_e32 v70, 1.0, v70
	v_rcp_f32_e32 v70, v70
	v_mul_f32_e32 v64, v69, v71
	v_fmamk_f32 v69, v174, 0x3a000000, v150
	v_mul_f32_e32 v68, v68, v64
	v_mul_f32_e32 v64, v67, v70
	v_mul_f32_e32 v70, 0x4b800000, v69
	v_cmp_gt_f32_e32 vcc, s40, v69
	v_mul_f32_e32 v67, v66, v64
	v_cvt_pk_bf16_f32 v64, v80, v79
	v_cvt_pk_bf16_f32 v65, v76, v74
	v_cvt_pk_bf16_f32 v66, v72, v73
	v_mov_b32_e32 v72, v56
	v_cndmask_b32_e32 v69, v69, v70, vcc
	v_rsq_f32_e32 v70, v69
	v_mov_b32_e32 v73, v60
	v_mov_b32_e32 v60, v57
	v_cvt_pk_bf16_f32 v67, v68, v67
	v_mul_f32_e32 v71, 0x45800000, v70
	v_cndmask_b32_e32 v70, v70, v71, vcc
	v_pk_mul_f32 v[72:73], v[72:73], v[70:71] op_sel_hi:[1,0]
	v_mad_i64_i32 v[68:69], s[4:5], v122, s41, v[120:121]
	v_mul_f32_e32 v56, 0xbfb8aa3b, v73
	v_exp_f32_e32 v71, v56
	s_nop 0
	v_pk_mul_f32 v[56:57], v[60:61], v[70:71] op_sel_hi:[1,0]
	s_nop 0
	v_mul_f32_e32 v60, 0xbfb8aa3b, v57
	v_exp_f32_e32 v74, v60
	v_lshl_add_u64 v[60:61], v[68:69], 0, v[112:113]
	v_add_f32_e32 v68, 1.0, v71
	v_rcp_f32_e32 v68, v68
	global_store_dwordx4 v[60:61], v[64:67], off
	v_mov_b32_e32 v61, v62
	v_add_f32_e32 v69, 1.0, v74
	v_mul_f32_e32 v60, v73, v68
	v_mul_f32_e32 v64, v72, v60
	v_mov_b32_e32 v60, v58
	v_pk_mul_f32 v[60:61], v[60:61], v[70:71] op_sel_hi:[1,0]
	v_mov_b32_e32 v62, v59
	v_mul_f32_e32 v58, 0xbfb8aa3b, v61
	v_rcp_f32_e32 v69, v69
	v_exp_f32_e32 v65, v58
	v_pk_mul_f32 v[58:59], v[62:63], v[70:71] op_sel_hi:[1,0]
	v_mul_f32_e32 v57, v57, v69
	v_mul_f32_e32 v62, 0xbfb8aa3b, v59
	v_exp_f32_e32 v62, v62
	v_mul_f32_e32 v63, v56, v57
	v_add_f32_e32 v56, 1.0, v65
	v_rcp_f32_e32 v65, v56
	v_add_f32_e32 v56, 1.0, v62
	v_rcp_f32_e32 v62, v56
	v_mov_b32_e32 v56, v48
	v_mov_b32_e32 v57, v52
	v_pk_mul_f32 v[56:57], v[56:57], v[70:71] op_sel_hi:[1,0]
	v_mul_f32_e32 v52, v61, v65
	v_mul_f32_e32 v48, 0xbfb8aa3b, v57
	v_exp_f32_e32 v48, v48
	v_mul_f32_e32 v60, v60, v52
	v_mov_b32_e32 v52, v49
	v_mul_f32_e32 v59, v59, v62
	v_add_f32_e32 v48, 1.0, v48
	v_rcp_f32_e32 v61, v48
	v_pk_mul_f32 v[48:49], v[52:53], v[70:71] op_sel_hi:[1,0]
	v_mul_f32_e32 v58, v58, v59
	v_mul_f32_e32 v52, 0xbfb8aa3b, v49
	v_exp_f32_e32 v52, v52
	v_mul_f32_e32 v53, v57, v61
	v_mul_f32_e32 v56, v56, v53
	v_mov_b32_e32 v53, v54
	v_add_f32_e32 v52, 1.0, v52
	v_rcp_f32_e32 v57, v52
	v_mov_b32_e32 v52, v50
	v_pk_mul_f32 v[52:53], v[52:53], v[70:71] op_sel_hi:[1,0]
; __device__ __forceinline__ unsigned pk_bf16(float lo, float hi) { unsigned r; asm volatile("v_cvt_pk_bf16_f32 %0, %1, %2" : "=v"(r) : "v"(lo), "v"(hi)); return r; }
; __device__ __forceinline__ float sigmoidf_(float x) { return __builtin_amdgcn_rcpf(1.0f + __expf(-x)); }
;     __device__ __forceinline__ void operator()(const f32x4 (&acc)[2][2][4][2], const Unit& u, int wr, int wc, int fr, int fq) const {
;     ...
;             for (int m = 0; m < 4; ++m) rs[ai][m] = rowsq[row0 + ai * 128 + m * 16];
; #pragma unroll
;         for (int ai = 0; ai < 2; ++ai)
; #pragma unroll
;             for (int m = 0; m < 4; ++m) {
;                 const int row = row0 + ai * 128 + m * 16;
;                 const float rstd = rsqrtf(rs[ai][m] * (1.0f / D) + RMS_EPS);
;                 f32x4 o[2];
; #pragma unroll
;                 for (int n = 0; n < 2; ++n)
; #pragma unroll
;                     for (int j = 0; j < 4; ++j) { const float gt = acc[ai][0][m][n][j] * rstd, up = acc[ai][1][m][n][j] * rstd; o[n][j] = gt * sigmoidf_(gt) * up; }
;                 u32x4 w; w.x = pk_bf16(o[0][0], o[0][1]); w.y = pk_bf16(o[0][2], o[0][3]); w.z = pk_bf16(o[1][0], o[1][1]); w.w = pk_bf16(o[1][2], o[1][3]);
;                 *(u32x4*)(U + (size_t)row * DFF + col0) = w;
	v_mov_b32_e32 v54, v51
	v_mul_f32_e32 v50, 0xbfb8aa3b, v53
	v_exp_f32_e32 v59, v50
	v_pk_mul_f32 v[50:51], v[54:55], v[70:71] op_sel_hi:[1,0]
	v_mul_f32_e32 v49, v49, v57
	v_mul_f32_e32 v54, 0xbfb8aa3b, v51
	v_exp_f32_e32 v54, v54
	v_add_f32_e32 v55, 1.0, v59
	v_rcp_f32_e32 v55, v55
	v_mul_f32_e32 v57, v48, v49
	v_add_f32_e32 v54, 1.0, v54
	v_rcp_f32_e32 v54, v54
	v_mul_f32_e32 v48, v53, v55
	v_fmamk_f32 v53, v153, 0x3a000000, v150
	v_mul_f32_e32 v52, v52, v48
	v_mul_f32_e32 v48, v51, v54
	v_mul_f32_e32 v54, 0x4b800000, v53
	v_cmp_gt_f32_e32 vcc, s40, v53
	v_mul_f32_e32 v51, v50, v48
	v_cvt_pk_bf16_f32 v48, v64, v63
	v_cvt_pk_bf16_f32 v49, v60, v58
	v_cvt_pk_bf16_f32 v50, v56, v57
	v_mov_b32_e32 v56, v40
	v_cndmask_b32_e32 v53, v53, v54, vcc
	v_rsq_f32_e32 v54, v53
	v_mov_b32_e32 v57, v44
	v_mov_b32_e32 v44, v41
	v_cvt_pk_bf16_f32 v51, v52, v51
	v_mul_f32_e32 v55, 0x45800000, v54
	v_cndmask_b32_e32 v54, v54, v55, vcc
	v_pk_mul_f32 v[56:57], v[56:57], v[54:55] op_sel_hi:[1,0]
	v_mad_i64_i32 v[52:53], s[4:5], v152, s41, v[120:121]
	v_mul_f32_e32 v40, 0xbfb8aa3b, v57
	v_exp_f32_e32 v55, v40
	s_nop 0
	v_pk_mul_f32 v[40:41], v[44:45], v[54:55] op_sel_hi:[1,0]
	s_nop 0
	v_mul_f32_e32 v44, 0xbfb8aa3b, v41
	v_exp_f32_e32 v58, v44
	v_lshl_add_u64 v[44:45], v[52:53], 0, v[112:113]
	v_add_f32_e32 v52, 1.0, v55
	v_rcp_f32_e32 v52, v52
	global_store_dwordx4 v[44:45], v[48:51], off
	v_mov_b32_e32 v45, v46
	v_add_f32_e32 v53, 1.0, v58
	v_mul_f32_e32 v44, v57, v52
	v_mul_f32_e32 v48, v56, v44
	v_mov_b32_e32 v44, v42
	v_pk_mul_f32 v[44:45], v[44:45], v[54:55] op_sel_hi:[1,0]
	v_mov_b32_e32 v46, v43
	v_mul_f32_e32 v42, 0xbfb8aa3b, v45
	v_rcp_f32_e32 v53, v53
	v_exp_f32_e32 v49, v42
	v_pk_mul_f32 v[42:43], v[46:47], v[54:55] op_sel_hi:[1,0]
	v_mul_f32_e32 v41, v41, v53
	v_mul_f32_e32 v46, 0xbfb8aa3b, v43
	v_exp_f32_e32 v46, v46
	v_mul_f32_e32 v47, v40, v41
	v_add_f32_e32 v40, 1.0, v49
	v_rcp_f32_e32 v49, v40
	v_add_f32_e32 v40, 1.0, v46
	v_rcp_f32_e32 v46, v40
	v_mov_b32_e32 v40, v32
	v_mov_b32_e32 v41, v36
	v_pk_mul_f32 v[40:41], v[40:41], v[54:55] op_sel_hi:[1,0]
	v_mul_f32_e32 v36, v45, v49
	v_mul_f32_e32 v32, 0xbfb8aa3b, v41
	v_exp_f32_e32 v32, v32
	v_mul_f32_e32 v44, v44, v36
	v_mov_b32_e32 v36, v33
	v_mul_f32_e32 v43, v43, v46
	v_add_f32_e32 v32, 1.0, v32
	v_rcp_f32_e32 v45, v32
	v_pk_mul_f32 v[32:33], v[36:37], v[54:55] op_sel_hi:[1,0]
	v_mul_f32_e32 v42, v42, v43
	v_mul_f32_e32 v36, 0xbfb8aa3b, v33
	v_exp_f32_e32 v36, v36
	v_mul_f32_e32 v37, v41, v45
	v_mul_f32_e32 v40, v40, v37
	v_mov_b32_e32 v37, v38
	v_add_f32_e32 v36, 1.0, v36
	v_rcp_f32_e32 v41, v36
	v_mov_b32_e32 v36, v34
	v_pk_mul_f32 v[36:37], v[36:37], v[54:55] op_sel_hi:[1,0]
	v_mov_b32_e32 v38, v35
	v_mul_f32_e32 v34, 0xbfb8aa3b, v37
	v_exp_f32_e32 v43, v34
	v_pk_mul_f32 v[34:35], v[38:39], v[54:55] op_sel_hi:[1,0]
	v_mul_f32_e32 v33, v33, v41
	v_mul_f32_e32 v38, 0xbfb8aa3b, v35
	v_exp_f32_e32 v38, v38
	v_add_f32_e32 v39, 1.0, v43
	v_rcp_f32_e32 v39, v39
	v_mul_f32_e32 v41, v32, v33
	v_add_f32_e32 v38, 1.0, v38
	v_rcp_f32_e32 v38, v38
	v_mul_f32_e32 v32, v37, v39
	v_fmamk_f32 v37, v151, 0x3a000000, v150
	v_mul_f32_e32 v36, v36, v32
	v_mul_f32_e32 v32, v35, v38
	v_mul_f32_e32 v38, 0x4b800000, v37
	v_cmp_gt_f32_e32 vcc, s40, v37
	v_mul_f32_e32 v35, v34, v32
	v_cvt_pk_bf16_f32 v32, v48, v47
	v_cvt_pk_bf16_f32 v33, v44, v42
	v_cvt_pk_bf16_f32 v34, v40, v41
	v_mov_b32_e32 v40, v24
	v_cndmask_b32_e32 v37, v37, v38, vcc
	v_rsq_f32_e32 v38, v37
	v_mov_b32_e32 v41, v28
	v_mov_b32_e32 v28, v25
	v_cvt_pk_bf16_f32 v35, v36, v35
	v_mul_f32_e32 v39, 0x45800000, v38
	v_cndmask_b32_e32 v38, v38, v39, vcc
	v_pk_mul_f32 v[40:41], v[40:41], v[38:39] op_sel_hi:[1,0]
	v_mad_i64_i32 v[36:37], s[4:5], v127, s41, v[120:121]
	v_mul_f32_e32 v24, 0xbfb8aa3b, v41
	v_exp_f32_e32 v39, v24
	s_nop 0
	v_pk_mul_f32 v[24:25], v[28:29], v[38:39] op_sel_hi:[1,0]
	s_nop 0
	v_mul_f32_e32 v28, 0xbfb8aa3b, v25
	v_exp_f32_e32 v42, v28
	v_lshl_add_u64 v[28:29], v[36:37], 0, v[112:113]
	v_add_f32_e32 v36, 1.0, v39
	v_rcp_f32_e32 v36, v36
	global_store_dwordx4 v[28:29], v[32:35], off
	v_mov_b32_e32 v29, v30
	v_add_f32_e32 v37, 1.0, v42
	v_mul_f32_e32 v28, v41, v36
	v_mul_f32_e32 v32, v40, v28
	v_mov_b32_e32 v28, v26
	v_pk_mul_f32 v[28:29], v[28:29], v[38:39] op_sel_hi:[1,0]
	v_mov_b32_e32 v30, v27
	v_mul_f32_e32 v26, 0xbfb8aa3b, v29
	v_rcp_f32_e32 v37, v37
	v_exp_f32_e32 v33, v26
	v_pk_mul_f32 v[26:27], v[30:31], v[38:39] op_sel_hi:[1,0]
; __device__ __forceinline__ unsigned pk_bf16(float lo, float hi) { unsigned r; asm volatile("v_cvt_pk_bf16_f32 %0, %1, %2" : "=v"(r) : "v"(lo), "v"(hi)); return r; }
; __device__ __forceinline__ float sigmoidf_(float x) { return __builtin_amdgcn_rcpf(1.0f + __expf(-x)); }
; #define PG8_WAIT_V(n) asm volatile("s_waitcnt vmcnt(" #n ")" ::: "memory")
; #define PG8_BAR __builtin_amdgcn_s_barrier()
; template <class Epi, class Sched>
; __device__ __forceinline__ void gemm_phase(LAS unsigned char* lds, const Gemm g, const Sched& S, const Epi& E) {
;     ...
;         if (!has_next) break;
; #pragma unroll
;         for (int a = 0; a < 2; ++a)
; #pragma unroll
;             for (int b = 0; b < 2; ++b)
; #pragma unroll
;                 for (int m = 0; m < 4; ++m)
; #pragma unroll
;                     for (int n = 0; n < 2; ++n) acc[a][b][m][n] = (f32x4){0.f, 0.f, 0.f, 0.f};
;         cur = nxt; cA = nA; cB = nB; ++ui;
;     }
;     PG8_WAIT_V(0);
;     if (wr == 0) PG8_BAR;
;     PG8_BAR;
;     __device__ __forceinline__ void operator()(const f32x4 (&acc)[2][2][4][2], const Unit& u, int wr, int wc, int fr, int fq) const {
;     ...
;             for (int m = 0; m < 4; ++m) rs[ai][m] = rowsq[row0 + ai * 128 + m * 16];
; #pragma unroll
;         for (int ai = 0; ai < 2; ++ai)
; #pragma unroll
;             for (int m = 0; m < 4; ++m) {
;                 const int row = row0 + ai * 128 + m * 16;
;                 const float rstd = rsqrtf(rs[ai][m] * (1.0f / D) + RMS_EPS);
;                 f32x4 o[2];
; #pragma unroll
;                 for (int n = 0; n < 2; ++n)
; #pragma unroll
;                     for (int j = 0; j < 4; ++j) { const float gt = acc[ai][0][m][n][j] * rstd, up = acc[ai][1][m][n][j] * rstd; o[n][j] = gt * sigmoidf_(gt) * up; }
;                 u32x4 w; w.x = pk_bf16(o[0][0], o[0][1]); w.y = pk_bf16(o[0][2], o[0][3]); w.z = pk_bf16(o[1][0], o[1][1]); w.w = pk_bf16(o[1][2], o[1][3]);
;                 *(u32x4*)(U + (size_t)row * DFF + col0) = w;
	v_mul_f32_e32 v25, v25, v37
	v_mul_f32_e32 v30, 0xbfb8aa3b, v27
	v_exp_f32_e32 v30, v30
	v_mul_f32_e32 v31, v24, v25
	v_add_f32_e32 v24, 1.0, v33
	v_rcp_f32_e32 v33, v24
	v_add_f32_e32 v24, 1.0, v30
	v_rcp_f32_e32 v30, v24
	v_mov_b32_e32 v24, v16
	v_mov_b32_e32 v25, v20
	v_pk_mul_f32 v[24:25], v[24:25], v[38:39] op_sel_hi:[1,0]
	v_mul_f32_e32 v20, v29, v33
	v_mul_f32_e32 v16, 0xbfb8aa3b, v25
	v_exp_f32_e32 v16, v16
	v_mul_f32_e32 v28, v28, v20
	v_mov_b32_e32 v20, v17
	v_mul_f32_e32 v27, v27, v30
	v_add_f32_e32 v16, 1.0, v16
	v_rcp_f32_e32 v29, v16
	v_pk_mul_f32 v[16:17], v[20:21], v[38:39] op_sel_hi:[1,0]
	v_mul_f32_e32 v26, v26, v27
	v_mul_f32_e32 v20, 0xbfb8aa3b, v17
	v_exp_f32_e32 v20, v20
	v_mul_f32_e32 v21, v25, v29
	v_mul_f32_e32 v24, v24, v21
	v_mov_b32_e32 v21, v22
	v_add_f32_e32 v20, 1.0, v20
	v_rcp_f32_e32 v25, v20
	v_mov_b32_e32 v20, v18
	v_pk_mul_f32 v[20:21], v[20:21], v[38:39] op_sel_hi:[1,0]
	v_mov_b32_e32 v22, v19
	v_mul_f32_e32 v18, 0xbfb8aa3b, v21
	v_exp_f32_e32 v27, v18
	v_pk_mul_f32 v[18:19], v[22:23], v[38:39] op_sel_hi:[1,0]
	v_mul_f32_e32 v17, v17, v25
	v_mul_f32_e32 v22, 0xbfb8aa3b, v19
	v_exp_f32_e32 v22, v22
	v_add_f32_e32 v23, 1.0, v27
	v_rcp_f32_e32 v23, v23
	v_mul_f32_e32 v25, v16, v17
	v_add_f32_e32 v22, 1.0, v22
	v_rcp_f32_e32 v22, v22
	v_mul_f32_e32 v16, v21, v23
	v_fmamk_f32 v21, v126, 0x3a000000, v150
	v_mul_f32_e32 v20, v20, v16
	v_mul_f32_e32 v16, v19, v22
	v_mul_f32_e32 v22, 0x4b800000, v21
	v_cmp_gt_f32_e32 vcc, s40, v21
	v_mul_f32_e32 v19, v18, v16
	v_cvt_pk_bf16_f32 v16, v32, v31
	v_cvt_pk_bf16_f32 v17, v28, v26
	v_cvt_pk_bf16_f32 v18, v24, v25
	v_mov_b32_e32 v24, v8
	v_cndmask_b32_e32 v21, v21, v22, vcc
	v_rsq_f32_e32 v22, v21
	v_mov_b32_e32 v25, v12
	v_mov_b32_e32 v12, v9
	v_cvt_pk_bf16_f32 v19, v20, v19
	v_mul_f32_e32 v23, 0x45800000, v22
	v_cndmask_b32_e32 v22, v22, v23, vcc
	v_pk_mul_f32 v[24:25], v[24:25], v[22:23] op_sel_hi:[1,0]
	v_mad_i64_i32 v[20:21], s[4:5], v125, s41, v[120:121]
	v_mul_f32_e32 v8, 0xbfb8aa3b, v25
	v_exp_f32_e32 v23, v8
	s_and_b64 vcc, exec, s[0:1]
	v_pk_mul_f32 v[8:9], v[12:13], v[22:23] op_sel_hi:[1,0]
	s_nop 0
	v_mul_f32_e32 v12, 0xbfb8aa3b, v9
	v_exp_f32_e32 v26, v12
	v_lshl_add_u64 v[12:13], v[20:21], 0, v[112:113]
	v_add_f32_e32 v20, 1.0, v23
	v_rcp_f32_e32 v20, v20
	global_store_dwordx4 v[12:13], v[16:19], off
	v_mov_b32_e32 v13, v14
	v_add_f32_e32 v21, 1.0, v26
	v_mul_f32_e32 v12, v25, v20
	v_mul_f32_e32 v16, v24, v12
	v_mov_b32_e32 v12, v10
	v_pk_mul_f32 v[12:13], v[12:13], v[22:23] op_sel_hi:[1,0]
	v_mov_b32_e32 v14, v11
	v_mul_f32_e32 v10, 0xbfb8aa3b, v13
	v_rcp_f32_e32 v21, v21
	v_exp_f32_e32 v17, v10
	v_pk_mul_f32 v[10:11], v[14:15], v[22:23] op_sel_hi:[1,0]
	v_mul_f32_e32 v9, v9, v21
	v_mul_f32_e32 v14, 0xbfb8aa3b, v11
	v_exp_f32_e32 v14, v14
	v_mul_f32_e32 v15, v8, v9
	v_add_f32_e32 v8, 1.0, v17
	v_rcp_f32_e32 v17, v8
	v_add_f32_e32 v8, 1.0, v14
	v_rcp_f32_e32 v14, v8
	v_mov_b32_e32 v8, v0
	v_mov_b32_e32 v9, v4
	v_pk_mul_f32 v[8:9], v[8:9], v[22:23] op_sel_hi:[1,0]
	v_mul_f32_e32 v4, v13, v17
	v_mul_f32_e32 v0, 0xbfb8aa3b, v9
	v_exp_f32_e32 v0, v0
	v_mul_f32_e32 v12, v12, v4
	v_mov_b32_e32 v4, v1
	v_mul_f32_e32 v11, v11, v14
	v_add_f32_e32 v0, 1.0, v0
	v_rcp_f32_e32 v13, v0
	v_pk_mul_f32 v[0:1], v[4:5], v[22:23] op_sel_hi:[1,0]
	v_mul_f32_e32 v10, v10, v11
	v_mul_f32_e32 v4, 0xbfb8aa3b, v1
	v_exp_f32_e32 v4, v4
	v_mul_f32_e32 v5, v9, v13
	v_mul_f32_e32 v8, v8, v5
	v_mov_b32_e32 v5, v6
	v_add_f32_e32 v4, 1.0, v4
	v_rcp_f32_e32 v9, v4
	v_mov_b32_e32 v4, v2
	v_pk_mul_f32 v[4:5], v[4:5], v[22:23] op_sel_hi:[1,0]
	v_mov_b32_e32 v6, v3
	v_mul_f32_e32 v2, 0xbfb8aa3b, v5
	v_exp_f32_e32 v11, v2
	v_pk_mul_f32 v[2:3], v[6:7], v[22:23] op_sel_hi:[1,0]
	v_mul_f32_e32 v1, v1, v9
	v_mul_f32_e32 v6, 0xbfb8aa3b, v3
	v_exp_f32_e32 v6, v6
	v_add_f32_e32 v7, 1.0, v11
	v_rcp_f32_e32 v7, v7
	v_mul_f32_e32 v9, v0, v1
	v_add_f32_e32 v6, 1.0, v6
	v_rcp_f32_e32 v6, v6
	v_mul_f32_e32 v0, v5, v7
	v_mul_f32_e32 v4, v4, v0
	v_mul_f32_e32 v0, v3, v6
	v_mul_f32_e32 v3, v2, v0
	v_cvt_pk_bf16_f32 v0, v16, v15
	v_cvt_pk_bf16_f32 v1, v12, v10
	v_cvt_pk_bf16_f32 v2, v8, v9
	v_cvt_pk_bf16_f32 v3, v4, v3
	v_mad_i64_i32 v[4:5], s[4:5], v123, s41, v[120:121]
	v_lshl_add_u64 v[4:5], v[4:5], 0, v[112:113]
	global_store_dwordx4 v[4:5], v[0:3], off
	s_cbranch_vccz .LBB0_1202
	s_nop 0
	s_nop 0
	s_nop 0
	s_nop 0
	s_nop 0
	s_nop 0
	s_nop 0
	s_nop 0
	s_waitcnt vmcnt(0)
	s_cmpk_gt_u32 s14, 0xff
	s_cbranch_scc1 .LBB0_1213
	s_barrier
